# P7 main loop back-edge rotation: k-step bookkeeping SALU moved ahead of the closing barrier (loop-edge edit), on the +4-placement stack
# baseline (speedup 1.0000x reference)
; template <class Epi, class Sched, bool ALIGN_EPI = false, bool SP2 = false>
; __device__ __forceinline__ void gemm_phase(PG8_LAS unsigned char* lds, const Gemm g, const Sched& S, const Epi& E) {
;     ...
;     for (;;) {
;         const bool has_next = S.next(ui + 1, nxt);
;         const char* nA = has_next ? (const char*)g.A + (size_t)nxt.pm * tstep + (size_t)nxt.kt0 * kstep : cA; const char* nB = has_next ? (const char*)g.Bt + (size_t)nxt.pn * tstep + (size_t)nxt.kt0 * kstep : cB;
;         const int nt = cur.nkt;
;         for (int t = 0; t < nt; t += 2) {
;             const bool last = (t == nt - 2);
;             const char* a1 = cA + (size_t)(t + 1) * kstep;
;             const char* a2 = last ? nA : cA + (size_t)(t + 2) * kstep; const char* b2 = last ? nB : cB + (size_t)(t + 2) * kstep;
;             const char* a3 = a2 + kstep; const char* b3 = b2 + kstep;
;             if (last && has_next) S.a_ready(nxt);
;     ...
;         if (cur.ks != -2) {
; #pragma unroll
;         for (int a = 0; a < 2; ++a)
; #pragma unroll
;             for (int b = 0; b < 2; ++b)
; #pragma unroll
;                 for (int m = 0; m < 4; ++m)
; #pragma unroll
;                     for (int n = 0; n < 2; ++n) acc[a][b][m][n] = (f32x4){0.f, 0.f, 0.f, 0.f};
;         }
;         cur = nxt; cA = nA; cB = nB; ++ui;
.LBB0_1486:
	s_ashr_i32 s21, s20, 31
	s_lshl_b64 s[2:3], s[20:21], 20
	s_add_u32 s42, s6, s2
	s_addc_u32 s43, s7, s3
	s_and_b64 s[2:3], s[40:41], exec
	s_cselect_b32 s21, s43, s49
	s_cselect_b32 s24, s42, s48
	s_ashr_i32 s19, s18, 31
	s_lshl_b64 s[2:3], s[18:19], 20
	s_add_u32 s44, s10, s2
	s_addc_u32 s45, s11, s3
	s_and_b64 s[2:3], s[40:41], exec
	s_cselect_b32 s19, s45, s23
	s_cselect_b32 s25, s44, s22
	s_add_u32 s55, s22, 0x100
	s_addc_u32 s56, s23, 0
	s_add_u32 s48, s48, 0x80080
	v_mov_b32_e32 v2, 0
	s_addc_u32 s49, s49, 0
	s_mov_b32 s57, -2
	v_mov_b32_e32 v3, v2
	v_mov_b32_e32 v4, v2
	v_mov_b32_e32 v5, v2
	v_mov_b32_e32 v10, v2
	v_mov_b32_e32 v11, v2
	v_mov_b32_e32 v12, v2
	v_mov_b32_e32 v13, v2
	v_mov_b32_e32 v18, v2
	v_mov_b32_e32 v19, v2
	v_mov_b32_e32 v20, v2
	v_mov_b32_e32 v21, v2
	v_mov_b32_e32 v26, v2
	v_mov_b32_e32 v27, v2
	v_mov_b32_e32 v28, v2
	v_mov_b32_e32 v29, v2
	s_waitcnt vmcnt(0)
	v_mov_b32_e32 v34, v2
	v_mov_b32_e32 v35, v2
	v_mov_b32_e32 v36, v2
	v_mov_b32_e32 v37, v2
	v_mov_b32_e32 v42, v2
	v_mov_b32_e32 v43, v2
	v_mov_b32_e32 v44, v2
	v_mov_b32_e32 v45, v2
	v_mov_b32_e32 v50, v2
	v_mov_b32_e32 v51, v2
	v_mov_b32_e32 v52, v2
	v_mov_b32_e32 v53, v2
	v_mov_b32_e32 v58, v2
	v_mov_b32_e32 v59, v2
	v_mov_b32_e32 v60, v2
	v_mov_b32_e32 v61, v2
	v_mov_b32_e32 v6, v2
	v_mov_b32_e32 v7, v2
	v_mov_b32_e32 v8, v2
	v_mov_b32_e32 v9, v2
	v_mov_b32_e32 v14, v2
	v_mov_b32_e32 v15, v2
	v_mov_b32_e32 v16, v2
	v_mov_b32_e32 v17, v2
	v_mov_b32_e32 v22, v2
	v_mov_b32_e32 v23, v2
	v_mov_b32_e32 v24, v2
	v_mov_b32_e32 v25, v2
	v_mov_b32_e32 v30, v2
	v_mov_b32_e32 v31, v2
	v_mov_b32_e32 v32, v2
	v_mov_b32_e32 v33, v2
	v_mov_b32_e32 v38, v2
	v_mov_b32_e32 v39, v2
	v_mov_b32_e32 v40, v2
	v_mov_b32_e32 v41, v2
	v_mov_b32_e32 v46, v2
	v_mov_b32_e32 v47, v2
	v_mov_b32_e32 v48, v2
	v_mov_b32_e32 v49, v2
	v_mov_b32_e32 v54, v2
	v_mov_b32_e32 v55, v2
	v_mov_b32_e32 v56, v2
	v_mov_b32_e32 v57, v2
	v_mov_b32_e32 v62, v2
	v_mov_b32_e32 v63, v2
	v_mov_b32_e32 v64, v2
	v_mov_b32_e32 v65, v2
	v_mov_b32_e32 v66, v2
	v_mov_b32_e32 v67, v2
	v_mov_b32_e32 v68, v2
	v_mov_b32_e32 v69, v2
	v_mov_b32_e32 v74, v2
	v_mov_b32_e32 v75, v2
	v_mov_b32_e32 v76, v2
	v_mov_b32_e32 v77, v2
	v_mov_b32_e32 v82, v2
	v_mov_b32_e32 v83, v2
	v_mov_b32_e32 v84, v2
	v_mov_b32_e32 v85, v2
	v_mov_b32_e32 v90, v2
	v_mov_b32_e32 v91, v2
	v_mov_b32_e32 v92, v2
	v_mov_b32_e32 v93, v2
	v_mov_b32_e32 v98, v2
	v_mov_b32_e32 v99, v2
	v_mov_b32_e32 v100, v2
	v_mov_b32_e32 v101, v2
	v_mov_b32_e32 v106, v2
	v_mov_b32_e32 v107, v2
	v_mov_b32_e32 v108, v2
	v_mov_b32_e32 v109, v2
	v_mov_b32_e32 v114, v2
	v_mov_b32_e32 v115, v2
	v_mov_b32_e32 v116, v2
	v_mov_b32_e32 v117, v2
	v_mov_b32_e32 v122, v2
	v_mov_b32_e32 v123, v2
	v_mov_b32_e32 v124, v2
	v_mov_b32_e32 v125, v2
	v_mov_b32_e32 v70, v2
	v_mov_b32_e32 v71, v2
	v_mov_b32_e32 v72, v2
	v_mov_b32_e32 v73, v2
	v_mov_b32_e32 v78, v2
	v_mov_b32_e32 v79, v2
	v_mov_b32_e32 v80, v2
	v_mov_b32_e32 v81, v2
	v_mov_b32_e32 v86, v2
	v_mov_b32_e32 v87, v2
	v_mov_b32_e32 v88, v2
	v_mov_b32_e32 v89, v2
	v_mov_b32_e32 v94, v2
	v_mov_b32_e32 v95, v2
	v_mov_b32_e32 v96, v2
	v_mov_b32_e32 v97, v2
	v_mov_b32_e32 v102, v2
	v_mov_b32_e32 v103, v2
	v_mov_b32_e32 v104, v2
	v_mov_b32_e32 v105, v2
	v_mov_b32_e32 v110, v2
	v_mov_b32_e32 v111, v2
	v_mov_b32_e32 v112, v2
	v_mov_b32_e32 v113, v2
	v_mov_b32_e32 v118, v2
	v_mov_b32_e32 v119, v2
	v_mov_b32_e32 v120, v2
	v_mov_b32_e32 v121, v2
	v_mov_b32_e32 v126, v2
	v_mov_b32_e32 v127, v2
	v_mov_b32_e32 v128, v2
	v_mov_b32_e32 v129, v2
	s_add_u32 s2, s48, 0xfff80080
	s_addc_u32 s3, s49, -1
	s_add_i32 s58, 0, 0x10000
	s_cmp_eq_u32 s57, 28
	s_cselect_b32 s51, s21, s3
	s_cselect_b32 s50, s24, s2
	s_cselect_b32 s23, s19, s56
	s_cselect_b32 s22, s25, s55
	s_add_i32 s59, 0, 0x14000
.LBB0_1487:
	v_add_u32_e32 v156, s58, v149
	v_add_u32_e32 v172, s59, v149
	ds_read_b128 v[140:143], v156
	ds_read_b128 v[144:147], v156 offset:1024
	ds_read_b128 v[152:155], v156 offset:2048
	ds_read_b128 v[156:159], v156 offset:3072
	ds_read_b128 v[160:163], v172
	ds_read_b128 v[164:167], v172 offset:1024
	ds_read_b128 v[168:171], v172 offset:2048
	ds_read_b128 v[172:175], v172 offset:3072
	v_lshl_add_u64 v[184:185], s[48:49], 0, v[138:139]
	s_add_i32 m0, s35, 0xc000
	ds_read_b128 v[176:179], v151
	ds_read_b128 v[180:183], v151 offset:1024
	ds_read_b128 v[200:203], v151 offset:2048
	ds_read_b128 v[204:207], v151 offset:3072
	ds_read_b128 v[208:211], v151 offset:4096
	ds_read_b128 v[212:215], v151 offset:5120
	ds_read_b128 v[216:219], v151 offset:6144
	ds_read_b128 v[232:235], v151 offset:7168
	global_load_lds_dwordx4 v[184:185], off
	v_lshl_add_u64 v[184:185], s[48:49], 0, v[136:137]
	s_add_i32 m0, s35, 0xe000
	s_nop 0
	global_load_lds_dwordx4 v[184:185], off
	s_waitcnt vmcnt(8)
	s_waitcnt lgkmcnt(0)
	s_barrier
; #define PG8_STAGE(bufoff, gbase, voff) do { _Pragma("unroll") for (int _i = 0; _i < 2; ++_i) \
;         __builtin_amdgcn_global_load_lds((const unsigned*)((const char*)(gbase) + (voff)[_i]), (PG8_LAS unsigned*)(lds + (bufoff) + ldsw + _i * 8192), 16, 0, 0); } while (0)
; #define PG8_LDA(dst, b, h) do { _Pragma("unroll") for (int m = 0; m < 4; ++m) _Pragma("unroll") for (int k = 0; k < 2; ++k) dst[m][k] = *(const PG8_LAS bf16x8*)(lds + PG8_SA(b, h) + aoff + m * 2048 + k * 1024); } while (0)
; #define PG8_LDB(dst, b, h) do { _Pragma("unroll") for (int n = 0; n < 2; ++n) _Pragma("unroll") for (int k = 0; k < 2; ++k) dst[n][k] = *(const PG8_LAS bf16x8*)(lds + PG8_SB(b, h) + boff + n * 2048 + k * 1024); } while (0)
; #define PG8_MMA(ai, bj, At, Bt) do { __builtin_amdgcn_s_setprio(1); _Pragma("unroll") for (int m = 0; m < 4; ++m) _Pragma("unroll") for (int n = 0; n < 2; ++n) _Pragma("unroll") for (int k = 0; k < 2; ++k) \
;         acc[ai][bj][m][n] = __builtin_amdgcn_mfma_f32_16x16x32_bf16(Bt[n][k], At[m][k], acc[ai][bj][m][n], 0, 0, 0); __builtin_amdgcn_s_setprio(0); } while (0)
; #define PG8_WAIT_V(n) asm volatile("s_waitcnt vmcnt(" #n ")" ::: "memory")
; #define PG8_WAIT_L(n) asm volatile("s_waitcnt lgkmcnt(" #n ")" ::: "memory")
; #define PG8_BAR __builtin_amdgcn_s_barrier()
; #define PG8_SCHED __builtin_amdgcn_sched_barrier(0)
; template <class Epi, class Sched, bool ALIGN_EPI = false, bool SP2 = false>
; __device__ __forceinline__ void gemm_phase(PG8_LAS unsigned char* lds, const Gemm g, const Sched& S, const Epi& E) {
;     ...
;             PG8_LDB(B0, 0, 0); PG8_LDB(B1, 0, 1); PG8_SCHED; PG8_LDA(At, 0, 0); PG8_STAGE(PG8_SA(1, 1), a1 + hstep, voffA);
;             PG8_WAIT_V(8); PG8_WAIT_L(0); PG8_BAR; PG8_MMA(0, 0, At, B0); PG8_MMA(0, 1, At, B1); PG8_BAR; PG8_SCHED;
;             PG8_LDA(At, 0, 1); PG8_STAGE(PG8_SB(0, 0), b2, voffB); PG8_STAGE(PG8_SB(0, 1), b2 + hstep, voffB); PG8_STAGE(PG8_SA(0, 0), a2, voffA);
;             PG8_WAIT_V(8); PG8_WAIT_L(0); PG8_BAR; PG8_MMA(1, 0, At, B0); PG8_MMA(1, 1, At, B1); PG8_BAR; PG8_SCHED;
	s_setprio 1
	s_waitcnt lgkmcnt(0)
	v_mfma_f32_16x16x32_bf16 v[126:129], v[140:143], v[176:179], v[126:129]
	v_mfma_f32_16x16x32_bf16 v[118:121], v[152:155], v[176:179], v[118:121]
	v_mfma_f32_16x16x32_bf16 v[110:113], v[140:143], v[200:203], v[110:113]
	v_mfma_f32_16x16x32_bf16 v[102:105], v[152:155], v[200:203], v[102:105]
	v_mfma_f32_16x16x32_bf16 v[94:97], v[140:143], v[208:211], v[94:97]
	v_mfma_f32_16x16x32_bf16 v[86:89], v[152:155], v[208:211], v[86:89]
	v_mfma_f32_16x16x32_bf16 v[78:81], v[140:143], v[216:219], v[78:81]
	v_mfma_f32_16x16x32_bf16 v[70:73], v[152:155], v[216:219], v[70:73]
	v_mfma_f32_16x16x32_bf16 v[126:129], v[144:147], v[180:183], v[126:129]
	v_mfma_f32_16x16x32_bf16 v[118:121], v[156:159], v[180:183], v[118:121]
	v_mfma_f32_16x16x32_bf16 v[110:113], v[144:147], v[204:207], v[110:113]
	v_mfma_f32_16x16x32_bf16 v[102:105], v[156:159], v[204:207], v[102:105]
	v_mfma_f32_16x16x32_bf16 v[94:97], v[144:147], v[212:215], v[94:97]
	v_mfma_f32_16x16x32_bf16 v[86:89], v[156:159], v[212:215], v[86:89]
	v_mfma_f32_16x16x32_bf16 v[78:81], v[144:147], v[232:235], v[78:81]
	v_mfma_f32_16x16x32_bf16 v[70:73], v[156:159], v[232:235], v[70:73]
	s_setprio 0
	s_setprio 1
	v_mfma_f32_16x16x32_bf16 v[122:125], v[160:163], v[176:179], v[122:125]
	v_mfma_f32_16x16x32_bf16 v[114:117], v[168:171], v[176:179], v[114:117]
	v_mfma_f32_16x16x32_bf16 v[106:109], v[160:163], v[200:203], v[106:109]
	v_mfma_f32_16x16x32_bf16 v[98:101], v[168:171], v[200:203], v[98:101]
	v_mfma_f32_16x16x32_bf16 v[90:93], v[160:163], v[208:211], v[90:93]
	v_mfma_f32_16x16x32_bf16 v[82:85], v[168:171], v[208:211], v[82:85]
	v_mfma_f32_16x16x32_bf16 v[74:77], v[160:163], v[216:219], v[74:77]
	v_mfma_f32_16x16x32_bf16 v[66:69], v[168:171], v[216:219], v[66:69]
	v_mfma_f32_16x16x32_bf16 v[122:125], v[164:167], v[180:183], v[122:125]
	v_mfma_f32_16x16x32_bf16 v[114:117], v[172:175], v[180:183], v[114:117]
	v_mfma_f32_16x16x32_bf16 v[106:109], v[164:167], v[204:207], v[106:109]
	v_mfma_f32_16x16x32_bf16 v[98:101], v[172:175], v[204:207], v[98:101]
	v_mfma_f32_16x16x32_bf16 v[90:93], v[164:167], v[212:215], v[90:93]
	v_mfma_f32_16x16x32_bf16 v[82:85], v[172:175], v[212:215], v[82:85]
	v_mfma_f32_16x16x32_bf16 v[74:77], v[164:167], v[232:235], v[74:77]
	v_mfma_f32_16x16x32_bf16 v[66:69], v[172:175], v[232:235], v[66:69]
	s_setprio 0
	s_barrier
	s_add_i32 s2, s58, s28
	v_lshl_add_u64 v[184:185], s[22:23], 0, v[0:1]
	s_mov_b32 m0, s2
	ds_read_b128 v[176:179], v151 offset:16384
	ds_read_b128 v[180:183], v151 offset:17408
	ds_read_b128 v[200:203], v151 offset:18432
	ds_read_b128 v[204:207], v151 offset:19456
	ds_read_b128 v[208:211], v151 offset:20480
	ds_read_b128 v[212:215], v151 offset:21504
	ds_read_b128 v[216:219], v151 offset:22528
	ds_read_b128 v[232:235], v151 offset:23552
	global_load_lds_dwordx4 v[184:185], off
	s_add_i32 m0, s2, 0x2000
	s_add_u32 s2, s22, 0x80000
	v_lshl_add_u64 v[236:237], s[22:23], 0, v[130:131]
	s_addc_u32 s3, s23, 0
	s_add_i32 s58, s59, s28
	global_load_lds_dwordx4 v[236:237], off
	v_lshl_add_u64 v[238:239], s[2:3], 0, v[0:1]
	s_mov_b32 m0, s58
	v_lshl_add_u64 v[240:241], s[50:51], 0, v[132:133]
	global_load_lds_dwordx4 v[238:239], off
	v_lshl_add_u64 v[238:239], s[2:3], 0, v[130:131]
	s_add_i32 m0, s58, 0x2000
	s_nop 0
	global_load_lds_dwordx4 v[238:239], off
	v_lshl_add_u64 v[238:239], s[50:51], 0, v[134:135]
	s_mov_b32 m0, s35
	s_nop 0
	global_load_lds_dwordx4 v[238:239], off
	s_mov_b32 m0, s36
	s_nop 0
	global_load_lds_dwordx4 v[240:241], off
	s_waitcnt vmcnt(8)
	s_waitcnt lgkmcnt(0)
	s_barrier
	s_setprio 1
	s_waitcnt lgkmcnt(0)
	v_mfma_f32_16x16x32_bf16 v[62:65], v[140:143], v[176:179], v[62:65]
	v_mfma_f32_16x16x32_bf16 v[54:57], v[152:155], v[176:179], v[54:57]
	v_mfma_f32_16x16x32_bf16 v[46:49], v[140:143], v[200:203], v[46:49]
	v_mfma_f32_16x16x32_bf16 v[38:41], v[152:155], v[200:203], v[38:41]
	v_mfma_f32_16x16x32_bf16 v[30:33], v[140:143], v[208:211], v[30:33]
	v_mfma_f32_16x16x32_bf16 v[22:25], v[152:155], v[208:211], v[22:25]
	v_mfma_f32_16x16x32_bf16 v[14:17], v[140:143], v[216:219], v[14:17]
	v_mfma_f32_16x16x32_bf16 v[6:9], v[152:155], v[216:219], v[6:9]
	v_mfma_f32_16x16x32_bf16 v[62:65], v[144:147], v[180:183], v[62:65]
	v_mfma_f32_16x16x32_bf16 v[54:57], v[156:159], v[180:183], v[54:57]
	v_mfma_f32_16x16x32_bf16 v[46:49], v[144:147], v[204:207], v[46:49]
	v_mfma_f32_16x16x32_bf16 v[38:41], v[156:159], v[204:207], v[38:41]
	v_mfma_f32_16x16x32_bf16 v[30:33], v[144:147], v[212:215], v[30:33]
	v_mfma_f32_16x16x32_bf16 v[22:25], v[156:159], v[212:215], v[22:25]
	v_mfma_f32_16x16x32_bf16 v[14:17], v[144:147], v[232:235], v[14:17]
	v_mfma_f32_16x16x32_bf16 v[6:9], v[156:159], v[232:235], v[6:9]
	s_setprio 0
	s_setprio 1
	v_mfma_f32_16x16x32_bf16 v[58:61], v[160:163], v[176:179], v[58:61]
	v_mfma_f32_16x16x32_bf16 v[50:53], v[168:171], v[176:179], v[50:53]
	v_mfma_f32_16x16x32_bf16 v[42:45], v[160:163], v[200:203], v[42:45]
	v_mfma_f32_16x16x32_bf16 v[34:37], v[168:171], v[200:203], v[34:37]
	v_mfma_f32_16x16x32_bf16 v[26:29], v[160:163], v[208:211], v[26:29]
	v_mfma_f32_16x16x32_bf16 v[18:21], v[168:171], v[208:211], v[18:21]
	v_mfma_f32_16x16x32_bf16 v[10:13], v[160:163], v[216:219], v[10:13]
	v_mfma_f32_16x16x32_bf16 v[2:5], v[168:171], v[216:219], v[2:5]
	v_mfma_f32_16x16x32_bf16 v[58:61], v[164:167], v[180:183], v[58:61]
	v_mfma_f32_16x16x32_bf16 v[50:53], v[172:175], v[180:183], v[50:53]
	v_mfma_f32_16x16x32_bf16 v[42:45], v[164:167], v[204:207], v[42:45]
	v_mfma_f32_16x16x32_bf16 v[34:37], v[172:175], v[204:207], v[34:37]
	v_mfma_f32_16x16x32_bf16 v[26:29], v[164:167], v[212:215], v[26:29]
	v_mfma_f32_16x16x32_bf16 v[18:21], v[172:175], v[212:215], v[18:21]
	v_mfma_f32_16x16x32_bf16 v[10:13], v[164:167], v[232:235], v[10:13]
	v_mfma_f32_16x16x32_bf16 v[2:5], v[172:175], v[232:235], v[2:5]
	s_setprio 0
	s_barrier
; #define PG8_STAGE(bufoff, gbase, voff) do { _Pragma("unroll") for (int _i = 0; _i < 2; ++_i) \
;         __builtin_amdgcn_global_load_lds((const unsigned*)((const char*)(gbase) + (voff)[_i]), (PG8_LAS unsigned*)(lds + (bufoff) + ldsw + _i * 8192), 16, 0, 0); } while (0)
; #define PG8_LDA(dst, b, h) do { _Pragma("unroll") for (int m = 0; m < 4; ++m) _Pragma("unroll") for (int k = 0; k < 2; ++k) dst[m][k] = *(const PG8_LAS bf16x8*)(lds + PG8_SA(b, h) + aoff + m * 2048 + k * 1024); } while (0)
; #define PG8_LDB(dst, b, h) do { _Pragma("unroll") for (int n = 0; n < 2; ++n) _Pragma("unroll") for (int k = 0; k < 2; ++k) dst[n][k] = *(const PG8_LAS bf16x8*)(lds + PG8_SB(b, h) + boff + n * 2048 + k * 1024); } while (0)
; #define PG8_MMA(ai, bj, At, Bt) do { __builtin_amdgcn_s_setprio(1); _Pragma("unroll") for (int m = 0; m < 4; ++m) _Pragma("unroll") for (int n = 0; n < 2; ++n) _Pragma("unroll") for (int k = 0; k < 2; ++k) \
;         acc[ai][bj][m][n] = __builtin_amdgcn_mfma_f32_16x16x32_bf16(Bt[n][k], At[m][k], acc[ai][bj][m][n], 0, 0, 0); __builtin_amdgcn_s_setprio(0); } while (0)
; #define PG8_WAIT_V(n) asm volatile("s_waitcnt vmcnt(" #n ")" ::: "memory")
; #define PG8_WAIT_L(n) asm volatile("s_waitcnt lgkmcnt(" #n ")" ::: "memory")
; #define PG8_BAR __builtin_amdgcn_s_barrier()
; #define PG8_SCHED __builtin_amdgcn_sched_barrier(0)
; template <class Epi, class Sched, bool ALIGN_EPI = false, bool SP2 = false>
; __device__ __forceinline__ void gemm_phase(PG8_LAS unsigned char* lds, const Gemm g, const Sched& S, const Epi& E) {
;     ...
;             PG8_LDB(B0, 1, 0); PG8_LDB(B1, 1, 1); PG8_SCHED; PG8_LDA(At, 1, 0); PG8_STAGE(PG8_SA(0, 1), a2 + hstep, voffA);
;             PG8_WAIT_V(8); PG8_WAIT_L(0); PG8_BAR; PG8_MMA(0, 0, At, B0); PG8_MMA(0, 1, At, B1); PG8_BAR; PG8_SCHED;
;             PG8_LDA(At, 1, 1); PG8_STAGE(PG8_SB(1, 0), b3, voffB); PG8_STAGE(PG8_SB(1, 1), b3 + hstep, voffB); PG8_STAGE(PG8_SA(1, 0), a3, voffA);
;             PG8_WAIT_V(8); PG8_WAIT_L(0); PG8_BAR; PG8_MMA(1, 0, At, B0); PG8_MMA(1, 1, At, B1); PG8_BAR; PG8_SCHED;
	s_add_i32 s58, 0, 0x18000
	s_add_i32 s59, 0, 0x1c000
	v_add_u32_e32 v156, s58, v149
	v_add_u32_e32 v172, s59, v149
	ds_read_b128 v[140:143], v156
	ds_read_b128 v[144:147], v156 offset:1024
	ds_read_b128 v[152:155], v156 offset:2048
	ds_read_b128 v[156:159], v156 offset:3072
	ds_read_b128 v[160:163], v172
	ds_read_b128 v[164:167], v172 offset:1024
	ds_read_b128 v[168:171], v172 offset:2048
	ds_read_b128 v[172:175], v172 offset:3072
	s_add_u32 s2, s50, 0x80000
	s_addc_u32 s3, s51, 0
	s_mov_b32 m0, s37
	v_lshl_add_u64 v[242:243], s[2:3], 0, v[134:135]
	ds_read_b128 v[176:179], v151 offset:32768
	ds_read_b128 v[180:183], v151 offset:33792
	ds_read_b128 v[200:203], v151 offset:34816
	ds_read_b128 v[204:207], v151 offset:35840
	ds_read_b128 v[208:211], v151 offset:36864
	ds_read_b128 v[212:215], v151 offset:37888
	ds_read_b128 v[216:219], v151 offset:38912
	ds_read_b128 v[232:235], v151 offset:39936
	global_load_lds_dwordx4 v[242:243], off
	v_lshl_add_u64 v[242:243], s[2:3], 0, v[132:133]
	s_mov_b32 m0, s38
	s_nop 0
	global_load_lds_dwordx4 v[242:243], off
	s_waitcnt vmcnt(8)
	s_waitcnt lgkmcnt(0)
	s_barrier
	s_setprio 1
	s_waitcnt lgkmcnt(0)
	v_mfma_f32_16x16x32_bf16 v[126:129], v[140:143], v[176:179], v[126:129]
	v_mfma_f32_16x16x32_bf16 v[118:121], v[152:155], v[176:179], v[118:121]
	v_mfma_f32_16x16x32_bf16 v[110:113], v[140:143], v[200:203], v[110:113]
	v_mfma_f32_16x16x32_bf16 v[102:105], v[152:155], v[200:203], v[102:105]
	v_mfma_f32_16x16x32_bf16 v[94:97], v[140:143], v[208:211], v[94:97]
	v_mfma_f32_16x16x32_bf16 v[86:89], v[152:155], v[208:211], v[86:89]
	v_mfma_f32_16x16x32_bf16 v[78:81], v[140:143], v[216:219], v[78:81]
	v_mfma_f32_16x16x32_bf16 v[70:73], v[152:155], v[216:219], v[70:73]
	v_mfma_f32_16x16x32_bf16 v[126:129], v[144:147], v[180:183], v[126:129]
	v_mfma_f32_16x16x32_bf16 v[118:121], v[156:159], v[180:183], v[118:121]
	v_mfma_f32_16x16x32_bf16 v[110:113], v[144:147], v[204:207], v[110:113]
	v_mfma_f32_16x16x32_bf16 v[102:105], v[156:159], v[204:207], v[102:105]
	v_mfma_f32_16x16x32_bf16 v[94:97], v[144:147], v[212:215], v[94:97]
	v_mfma_f32_16x16x32_bf16 v[86:89], v[156:159], v[212:215], v[86:89]
	v_mfma_f32_16x16x32_bf16 v[78:81], v[144:147], v[232:235], v[78:81]
	v_mfma_f32_16x16x32_bf16 v[70:73], v[156:159], v[232:235], v[70:73]
	s_setprio 0
	s_setprio 1
	v_mfma_f32_16x16x32_bf16 v[122:125], v[160:163], v[176:179], v[122:125]
	v_mfma_f32_16x16x32_bf16 v[114:117], v[168:171], v[176:179], v[114:117]
	v_mfma_f32_16x16x32_bf16 v[106:109], v[160:163], v[200:203], v[106:109]
	v_mfma_f32_16x16x32_bf16 v[98:101], v[168:171], v[200:203], v[98:101]
	v_mfma_f32_16x16x32_bf16 v[90:93], v[160:163], v[208:211], v[90:93]
	v_mfma_f32_16x16x32_bf16 v[82:85], v[168:171], v[208:211], v[82:85]
	v_mfma_f32_16x16x32_bf16 v[74:77], v[160:163], v[216:219], v[74:77]
	v_mfma_f32_16x16x32_bf16 v[66:69], v[168:171], v[216:219], v[66:69]
	v_mfma_f32_16x16x32_bf16 v[122:125], v[164:167], v[180:183], v[122:125]
	v_mfma_f32_16x16x32_bf16 v[114:117], v[172:175], v[180:183], v[114:117]
	v_mfma_f32_16x16x32_bf16 v[106:109], v[164:167], v[204:207], v[106:109]
	v_mfma_f32_16x16x32_bf16 v[98:101], v[172:175], v[204:207], v[98:101]
	v_mfma_f32_16x16x32_bf16 v[90:93], v[164:167], v[212:215], v[90:93]
	v_mfma_f32_16x16x32_bf16 v[82:85], v[172:175], v[212:215], v[82:85]
	v_mfma_f32_16x16x32_bf16 v[74:77], v[164:167], v[232:235], v[74:77]
	v_mfma_f32_16x16x32_bf16 v[66:69], v[172:175], v[232:235], v[66:69]
	s_setprio 0
	s_barrier
	s_add_i32 s2, s58, s28
	v_lshl_add_u64 v[184:185], v[184:185], 0, s[0:1]
	s_mov_b32 m0, s2
	ds_read_b128 v[176:179], v151 offset:49152
	ds_read_b128 v[180:183], v151 offset:50176
	ds_read_b128 v[200:203], v151 offset:51200
	ds_read_b128 v[204:207], v151 offset:52224
	ds_read_b128 v[208:211], v151 offset:53248
	ds_read_b128 v[212:215], v151 offset:54272
	ds_read_b128 v[216:219], v151 offset:55296
	ds_read_b128 v[232:235], v151 offset:56320
	global_load_lds_dwordx4 v[184:185], off
	s_add_i32 m0, s2, 0x2000
	s_add_u32 s2, s22, 0x80080
	v_lshl_add_u64 v[184:185], v[236:237], 0, s[0:1]
	s_addc_u32 s3, s23, 0
	s_add_i32 s22, s59, s28
	global_load_lds_dwordx4 v[184:185], off
	v_lshl_add_u64 v[184:185], s[2:3], 0, v[0:1]
	s_mov_b32 m0, s22
	s_nop 0
	global_load_lds_dwordx4 v[184:185], off
	v_lshl_add_u64 v[184:185], s[2:3], 0, v[130:131]
	s_add_i32 m0, s22, 0x2000
	s_nop 0
	global_load_lds_dwordx4 v[184:185], off
	v_lshl_add_u64 v[184:185], v[238:239], 0, s[0:1]
	s_mov_b32 m0, s47
	s_nop 0
	global_load_lds_dwordx4 v[184:185], off
	v_lshl_add_u64 v[184:185], v[240:241], 0, s[0:1]
	s_mov_b32 m0, s52
	s_nop 0
	global_load_lds_dwordx4 v[184:185], off
	s_waitcnt vmcnt(8)
	s_waitcnt lgkmcnt(0)
	s_barrier
; #define PG8_BAR __builtin_amdgcn_s_barrier()
; template <class Epi, class Sched, bool ALIGN_EPI = false, bool SP2 = false>
; __device__ __forceinline__ void gemm_phase(PG8_LAS unsigned char* lds, const Gemm g, const Sched& S, const Epi& E) {
;     ...
;             PG8_WAIT_V(8); PG8_WAIT_L(0); PG8_BAR; PG8_MMA(1, 0, At, B0); PG8_MMA(1, 1, At, B1); PG8_BAR; PG8_SCHED;
;             } else {
;             PG8_LDB(B0, 0, 0); PG8_SCHED; PG8_LDA(At, 0, 0); PG8_STAGE(PG8_SA(1, 1), a1 + hstep, voffA);
;             PG8_WAIT_L(8); PG8_BAR; PG8_WAIT_L(0); PG8_MMA(0, 0, At, B0); PG8_BAR; PG8_SCHED;
;             PG8_LDB(B1, 0, 1); PG8_STAGE(PG8_SB(0, 0), b2, voffB);
;             PG8_BAR; PG8_WAIT_L(0); PG8_MMA(0, 1, At, B1); PG8_BAR;
;             PG8_LDA(At, 0, 1); PG8_STAGE(PG8_SA(0, 0), a2, voffA);
;             PG8_BAR; PG8_WAIT_L(0); PG8_MMA(1, 0, At, B0); PG8_BAR; PG8_SCHED;
;             PG8_STAGE(PG8_SB(0, 1), b2 + hstep, voffB);
;             PG8_WAIT_V(6); PG8_BAR; PG8_MMA(1, 1, At, B1); PG8_BAR;
;             PG8_LDB(B0, 1, 0); PG8_SCHED; PG8_LDA(At, 1, 0); PG8_STAGE(PG8_SA(0, 1), a2 + hstep, voffA);
;             PG8_WAIT_L(8); PG8_BAR; PG8_WAIT_L(0); PG8_MMA(0, 0, At, B0); PG8_BAR; PG8_SCHED;
;             PG8_LDB(B1, 1, 1); PG8_STAGE(PG8_SB(1, 0), b3, voffB);
;             PG8_BAR; PG8_WAIT_L(0); PG8_MMA(0, 1, At, B1); PG8_BAR;
;             PG8_LDA(At, 1, 1); PG8_STAGE(PG8_SA(1, 0), a3, voffA);
;             PG8_BAR; PG8_WAIT_L(0); PG8_MMA(1, 0, At, B0); PG8_BAR; PG8_SCHED;
;             PG8_STAGE(PG8_SB(1, 1), b3 + hstep, voffB);
;             PG8_WAIT_V(6); PG8_BAR; PG8_MMA(1, 1, At, B1); PG8_BAR;
;             }
;         }
;         if constexpr (ALIGN_EPI) { if (wr == 0) PG8_BAR; }
;     __device__ __forceinline__ void operator()(const f32x4 (&acc)[2][2][4][2], const Unit& u, int wr, int wc, int fr, int fq) const {
;         const int row0 = u.pm * BM + wr * 64 + fr, col0 = u.pn * HALF + wc * 32 + 8 * fq;
;         float rs[2][4];
; #pragma unroll
;         for (int ai = 0; ai < 2; ++ai)
; #pragma unroll
;             for (int m = 0; m < 4; ++m) rs[ai][m] = ssq[row0 + ai * HALF + m * 16];
; #pragma unroll
;         for (int ai = 0; ai < 2; ++ai)
; #pragma unroll
;             for (int m = 0; m < 4; ++m) { bf16_t* rowp = O + (size_t)(row0 + ai * HALF + m * 16) * DFF + col0; const float rsv = rsqrtf(rs[ai][m] * (1.f / D) + EPS);
	s_setprio 1
	s_waitcnt lgkmcnt(0)
	v_mfma_f32_16x16x32_bf16 v[62:65], v[140:143], v[176:179], v[62:65]
	v_mfma_f32_16x16x32_bf16 v[54:57], v[152:155], v[176:179], v[54:57]
	v_mfma_f32_16x16x32_bf16 v[46:49], v[140:143], v[200:203], v[46:49]
	v_mfma_f32_16x16x32_bf16 v[38:41], v[152:155], v[200:203], v[38:41]
	v_mfma_f32_16x16x32_bf16 v[30:33], v[140:143], v[208:211], v[30:33]
	v_mfma_f32_16x16x32_bf16 v[22:25], v[152:155], v[208:211], v[22:25]
	v_mfma_f32_16x16x32_bf16 v[14:17], v[140:143], v[216:219], v[14:17]
	v_mfma_f32_16x16x32_bf16 v[6:9], v[152:155], v[216:219], v[6:9]
	v_mfma_f32_16x16x32_bf16 v[62:65], v[144:147], v[180:183], v[62:65]
	v_mfma_f32_16x16x32_bf16 v[54:57], v[156:159], v[180:183], v[54:57]
	v_mfma_f32_16x16x32_bf16 v[46:49], v[144:147], v[204:207], v[46:49]
	v_mfma_f32_16x16x32_bf16 v[38:41], v[156:159], v[204:207], v[38:41]
	v_mfma_f32_16x16x32_bf16 v[30:33], v[144:147], v[212:215], v[30:33]
	v_mfma_f32_16x16x32_bf16 v[22:25], v[156:159], v[212:215], v[22:25]
	v_mfma_f32_16x16x32_bf16 v[14:17], v[144:147], v[232:235], v[14:17]
	v_mfma_f32_16x16x32_bf16 v[6:9], v[156:159], v[232:235], v[6:9]
	s_setprio 0
	s_setprio 1
	v_mfma_f32_16x16x32_bf16 v[58:61], v[160:163], v[176:179], v[58:61]
	v_mfma_f32_16x16x32_bf16 v[50:53], v[168:171], v[176:179], v[50:53]
	v_mfma_f32_16x16x32_bf16 v[42:45], v[160:163], v[200:203], v[42:45]
	v_mfma_f32_16x16x32_bf16 v[34:37], v[168:171], v[200:203], v[34:37]
	v_mfma_f32_16x16x32_bf16 v[26:29], v[160:163], v[208:211], v[26:29]
	v_mfma_f32_16x16x32_bf16 v[18:21], v[168:171], v[208:211], v[18:21]
	v_mfma_f32_16x16x32_bf16 v[10:13], v[160:163], v[216:219], v[10:13]
	v_mfma_f32_16x16x32_bf16 v[2:5], v[168:171], v[216:219], v[2:5]
	v_mfma_f32_16x16x32_bf16 v[58:61], v[164:167], v[180:183], v[58:61]
	v_mfma_f32_16x16x32_bf16 v[50:53], v[172:175], v[180:183], v[50:53]
	v_mfma_f32_16x16x32_bf16 v[42:45], v[164:167], v[204:207], v[42:45]
	v_mfma_f32_16x16x32_bf16 v[34:37], v[172:175], v[204:207], v[34:37]
	v_mfma_f32_16x16x32_bf16 v[26:29], v[164:167], v[212:215], v[26:29]
	v_mfma_f32_16x16x32_bf16 v[18:21], v[172:175], v[212:215], v[18:21]
	v_mfma_f32_16x16x32_bf16 v[10:13], v[164:167], v[232:235], v[10:13]
	v_mfma_f32_16x16x32_bf16 v[2:5], v[172:175], v[232:235], v[2:5]
	s_setprio 0
	s_add_i32 s57, s57, 2
	s_add_u32 s55, s55, 0x100
	s_addc_u32 s56, s56, 0
	s_add_u32 s48, s48, 0x100
	s_addc_u32 s49, s49, 0
	s_add_u32 s2, s48, 0xfff80080
	s_addc_u32 s3, s49, -1
	s_add_i32 s58, 0, 0x10000
	s_cmp_eq_u32 s57, 28
	s_cselect_b32 s51, s21, s3
	s_cselect_b32 s50, s24, s2
	s_cselect_b32 s23, s19, s56
	s_cselect_b32 s22, s25, s55
	s_add_i32 s59, 0, 0x14000
	s_cmp_gt_u32 s57, 29
	s_barrier
	s_cbranch_scc0 .LBB0_1487
	s_and_b64 vcc, exec, s[16:17]
	s_cbranch_vccz .LBB0_1490
	s_barrier
.LBB0_1490:
	v_lshl_add_u32 v144, s46, 8, v148
	v_ashrrev_i32_e32 v145, 31, v144
	v_lshl_add_u64 v[140:141], v[144:145], 2, s[12:13]
	flat_load_dword v146, v[140:141]
	flat_load_dword v164, v[140:141] offset:64
	flat_load_dword v162, v[140:141] offset:128
	flat_load_dword v160, v[140:141] offset:192
	flat_load_dword v158, v[140:141] offset:512
	flat_load_dword v156, v[140:141] offset:576
	flat_load_dword v154, v[140:141] offset:640
	flat_load_dword v152, v[140:141] offset:704
	v_mov_b32_e32 v166, v126
	v_lshl_or_b32 v142, s54, 7, v150
	v_ashrrev_i32_e32 v143, 31, v142
	v_mov_b64_e32 v[140:141], s[8:9]
	v_or_b32_e32 v165, 16, v144
	v_or_b32_e32 v163, 32, v144
	v_or_b32_e32 v161, 48, v144
	v_add_u32_e32 v159, 0x80, v144
	v_add_u32_e32 v157, 0x90, v144
	v_add_u32_e32 v155, 0xa0, v144
	v_add_u32_e32 v153, 0xb0, v144
	v_mad_i64_i32 v[144:145], s[2:3], v144, s34, v[140:141]
	s_mov_b64 s[22:23], -1
	s_mov_b64 s[56:57], s[94:95]
	s_waitcnt vmcnt(0) lgkmcnt(0)
	v_fmamk_f32 v146, v146, 0x3a000000, v223
	v_cmp_gt_f32_e32 vcc, s29, v146
	v_mul_f32_e32 v147, 0x4b800000, v146
	s_nop 0
	v_cndmask_b32_e32 v146, v146, v147, vcc
	v_rsq_f32_e32 v146, v146
	s_nop 0
	v_mul_f32_e32 v147, 0x45800000, v146
	v_cndmask_b32_e32 v146, v146, v147, vcc
	v_mul_f32_e32 v168, 0xbfb8aa3b, v146
	v_mul_f32_e32 v147, v146, v146
	v_mul_f32_e32 v146, v126, v168
	v_exp_f32_e32 v146, v146
	s_nop 0
	v_add_f32_e32 v146, 1.0, v146
	v_rcp_f32_e32 v167, v146
	v_mov_b32_e32 v146, v122
	v_mul_f32_e32 v122, v127, v168
	v_exp_f32_e32 v122, v122
	v_pk_mul_f32 v[166:167], v[146:147], v[166:167]
	v_mov_b32_e32 v146, v123
	v_mul_f32_e32 v126, v166, v167
	v_add_f32_e32 v122, 1.0, v122
	v_rcp_f32_e32 v167, v122
	v_mov_b32_e32 v166, v127
	v_pk_mul_f32 v[122:123], v[146:147], v[166:167]
	s_nop 0
	v_mul_f32_e32 v127, v122, v123
	v_mul_f32_e32 v122, v128, v168
	v_exp_f32_e32 v122, v122
	v_mov_b32_e32 v146, v124
	v_add_f32_e32 v122, 1.0, v122
	v_rcp_f32_e32 v123, v122
	v_mov_b32_e32 v122, v128
	v_pk_mul_f32 v[122:123], v[146:147], v[122:123]
	s_nop 0
	v_mul_f32_e32 v124, v122, v123
	v_mul_f32_e32 v122, v129, v168
	v_exp_f32_e32 v122, v122
	v_mov_b32_e32 v146, v125
	v_add_f32_e32 v122, 1.0, v122
	v_rcp_f32_e32 v123, v122
	v_mov_b32_e32 v122, v129
	v_pk_mul_f32 v[122:123], v[146:147], v[122:123]
	s_nop 0
	v_mul_f32_e32 v125, v122, v123
	v_mul_f32_e32 v122, v118, v168
	v_exp_f32_e32 v122, v122
	v_mov_b32_e32 v146, v114
	v_mul_f32_e32 v114, v119, v168
	v_exp_f32_e32 v114, v114
	v_add_f32_e32 v122, 1.0, v122
	v_rcp_f32_e32 v123, v122
	v_mov_b32_e32 v122, v118
	v_add_f32_e32 v114, 1.0, v114
	v_pk_mul_f32 v[122:123], v[146:147], v[122:123]
	s_nop 0
	v_mul_f32_e32 v118, v122, v123
	v_rcp_f32_e32 v123, v114
	v_mov_b32_e32 v146, v115
	v_mov_b32_e32 v122, v119
	v_pk_mul_f32 v[114:115], v[146:147], v[122:123]
	s_nop 0
	v_mul_f32_e32 v119, v114, v115
	v_mul_f32_e32 v114, v120, v168
	v_exp_f32_e32 v114, v114
; __device__ __forceinline__ unsigned pk2(float lo, float hi) { unsigned r; asm volatile("v_cvt_pk_bf16_f32 %0, %1, %2" : "=v"(r) : "v"(lo), "v"(hi)); return r; }
;     __device__ __forceinline__ void operator()(const f32x4 (&acc)[2][2][4][2], const Unit& u, int wr, int wc, int fr, int fq) const {
;     ...
; #pragma unroll
;         for (int ai = 0; ai < 2; ++ai)
; #pragma unroll
;             for (int m = 0; m < 4; ++m) { bf16_t* rowp = O + (size_t)(row0 + ai * HALF + m * 16) * DFF + col0; const float rsv = rsqrtf(rs[ai][m] * (1.f / D) + EPS);
;                 const float rs2 = rsv * rsv, nrs = -1.4426950409f * rsv;
;                 float v[8];
; #pragma unroll
;                 for (int n = 0; n < 2; ++n)
; #pragma unroll
;                     for (int j = 0; j < 4; ++j) {
;                         const float g0 = acc[ai][0][m][n][j], u0 = acc[ai][1][m][n][j];
;                         v[n * 4 + j] = (g0 * u0) * (rs2 * __builtin_amdgcn_rcpf(1.0f + __builtin_amdgcn_exp2f(g0 * nrs))); }
;                 u32x4 w; w.x = pk2(v[0], v[1]); w.y = pk2(v[2], v[3]); w.z = pk2(v[4], v[5]); w.w = pk2(v[6], v[7]);
;                 *(u32x4*)rowp = w; }
	v_mov_b32_e32 v146, v116
	v_cvt_pk_bf16_f32 v116, v126, v127
	v_add_f32_e32 v114, 1.0, v114
	v_rcp_f32_e32 v115, v114
	v_mov_b32_e32 v114, v120
	v_pk_mul_f32 v[114:115], v[146:147], v[114:115]
	s_nop 0
	v_mul_f32_e32 v122, v114, v115
	v_mul_f32_e32 v114, v121, v168
	v_exp_f32_e32 v114, v114
	v_mov_b32_e32 v146, v117
	v_cvt_pk_bf16_f32 v117, v124, v125
	v_cvt_pk_bf16_f32 v118, v118, v119
	v_add_f32_e32 v114, 1.0, v114
	v_rcp_f32_e32 v115, v114
	v_mov_b32_e32 v114, v121
	v_pk_mul_f32 v[114:115], v[146:147], v[114:115]
	s_nop 0
	v_mul_f32_e32 v123, v114, v115
	v_lshlrev_b64 v[114:115], 1, v[142:143]
	v_lshl_add_u64 v[120:121], v[144:145], 0, v[114:115]
	v_cvt_pk_bf16_f32 v119, v122, v123
	flat_store_dwordx4 v[120:121], v[116:119]
	v_mov_b32_e32 v120, v110
	s_nop 0
	v_fmamk_f32 v118, v164, 0x3a000000, v223
	v_cmp_gt_f32_e32 vcc, s29, v118
	v_mul_f32_e32 v119, 0x4b800000, v118
	v_mad_i64_i32 v[116:117], s[2:3], v165, s34, v[140:141]
	v_cndmask_b32_e32 v118, v118, v119, vcc
	v_rsq_f32_e32 v118, v118
	s_nop 0
	v_mul_f32_e32 v119, 0x45800000, v118
	v_cndmask_b32_e32 v118, v118, v119, vcc
	v_mul_f32_e32 v122, 0xbfb8aa3b, v118
	v_mul_f32_e32 v119, v118, v118
	v_mul_f32_e32 v118, v110, v122
	v_exp_f32_e32 v118, v118
	s_nop 0
	v_add_f32_e32 v118, 1.0, v118
	v_rcp_f32_e32 v121, v118
	v_mov_b32_e32 v118, v106
	v_mul_f32_e32 v106, v111, v122
	v_exp_f32_e32 v106, v106
	v_pk_mul_f32 v[120:121], v[118:119], v[120:121]
	v_mov_b32_e32 v118, v107
	v_mul_f32_e32 v110, v120, v121
	v_add_f32_e32 v106, 1.0, v106
	v_rcp_f32_e32 v121, v106
	v_mov_b32_e32 v120, v111
	v_pk_mul_f32 v[106:107], v[118:119], v[120:121]
	s_nop 0
	v_mul_f32_e32 v111, v106, v107
	v_mul_f32_e32 v106, v112, v122
	v_exp_f32_e32 v106, v106
	v_mov_b32_e32 v118, v108
	v_add_f32_e32 v106, 1.0, v106
	v_rcp_f32_e32 v107, v106
	v_mov_b32_e32 v106, v112
	v_pk_mul_f32 v[106:107], v[118:119], v[106:107]
	s_nop 0
	v_mul_f32_e32 v108, v106, v107
	v_mul_f32_e32 v106, v113, v122
	v_exp_f32_e32 v106, v106
	v_mov_b32_e32 v118, v109
	v_add_f32_e32 v106, 1.0, v106
	v_rcp_f32_e32 v107, v106
	v_mov_b32_e32 v106, v113
	v_pk_mul_f32 v[106:107], v[118:119], v[106:107]
	s_nop 0
	v_mul_f32_e32 v109, v106, v107
	v_mul_f32_e32 v106, v102, v122
	v_exp_f32_e32 v106, v106
	v_mov_b32_e32 v118, v98
	v_mul_f32_e32 v98, v103, v122
	v_exp_f32_e32 v98, v98
	v_add_f32_e32 v106, 1.0, v106
	v_rcp_f32_e32 v107, v106
	v_mov_b32_e32 v106, v102
	v_add_f32_e32 v98, 1.0, v98
	v_pk_mul_f32 v[106:107], v[118:119], v[106:107]
	s_nop 0
	v_mul_f32_e32 v112, v106, v107
	v_rcp_f32_e32 v107, v98
	v_mov_b32_e32 v118, v99
	v_mov_b32_e32 v106, v103
	v_lshl_add_u64 v[102:103], v[116:117], 0, v[114:115]
	v_pk_mul_f32 v[98:99], v[118:119], v[106:107]
	v_mov_b32_e32 v118, v100
	v_mul_f32_e32 v106, v98, v99
	v_mul_f32_e32 v98, v104, v122
	v_exp_f32_e32 v98, v98
	s_nop 0
	v_add_f32_e32 v98, 1.0, v98
	v_rcp_f32_e32 v99, v98
	v_mov_b32_e32 v98, v104
	v_pk_mul_f32 v[98:99], v[118:119], v[98:99]
	s_nop 0
	v_mul_f32_e32 v104, v98, v99
	v_mul_f32_e32 v98, v105, v122
	v_exp_f32_e32 v98, v98
	v_mov_b32_e32 v118, v101
	v_add_f32_e32 v98, 1.0, v98
	v_rcp_f32_e32 v99, v98
	v_mov_b32_e32 v98, v105
	v_pk_mul_f32 v[98:99], v[118:119], v[98:99]
	s_nop 0
	v_mul_f32_e32 v101, v98, v99
	v_cvt_pk_bf16_f32 v98, v110, v111
	v_cvt_pk_bf16_f32 v99, v108, v109
	v_cvt_pk_bf16_f32 v100, v112, v106
	v_cvt_pk_bf16_f32 v101, v104, v101
	flat_store_dwordx4 v[102:103], v[98:101]
	v_mov_b32_e32 v102, v94
	s_nop 0
	v_fmamk_f32 v100, v162, 0x3a000000, v223
	v_cmp_gt_f32_e32 vcc, s29, v100
	v_mul_f32_e32 v101, 0x4b800000, v100
	v_mad_i64_i32 v[98:99], s[2:3], v163, s34, v[140:141]
	v_cndmask_b32_e32 v100, v100, v101, vcc
	v_rsq_f32_e32 v100, v100
	s_nop 0
	v_mul_f32_e32 v101, 0x45800000, v100
	v_cndmask_b32_e32 v100, v100, v101, vcc
	v_mul_f32_e32 v104, 0xbfb8aa3b, v100
	v_mul_f32_e32 v101, v100, v100
	v_mul_f32_e32 v100, v94, v104
	v_exp_f32_e32 v100, v100
	s_nop 0
	v_add_f32_e32 v100, 1.0, v100
	v_rcp_f32_e32 v103, v100
	v_mov_b32_e32 v100, v90
	v_mul_f32_e32 v90, v95, v104
	v_exp_f32_e32 v90, v90
	v_pk_mul_f32 v[102:103], v[100:101], v[102:103]
	v_mov_b32_e32 v100, v91
	v_mul_f32_e32 v94, v102, v103
	v_add_f32_e32 v90, 1.0, v90
	v_rcp_f32_e32 v103, v90
	v_mov_b32_e32 v102, v95
	v_pk_mul_f32 v[90:91], v[100:101], v[102:103]
	s_nop 0
	v_mul_f32_e32 v95, v90, v91
	v_mul_f32_e32 v90, v96, v104
	v_exp_f32_e32 v90, v90
	v_mov_b32_e32 v100, v92
	v_add_f32_e32 v90, 1.0, v90
	v_rcp_f32_e32 v91, v90
	v_mov_b32_e32 v90, v96
	v_pk_mul_f32 v[90:91], v[100:101], v[90:91]
	s_nop 0
	v_mul_f32_e32 v92, v90, v91
	v_mul_f32_e32 v90, v97, v104
	v_exp_f32_e32 v90, v90
	v_mov_b32_e32 v100, v93
	v_add_f32_e32 v90, 1.0, v90
	v_rcp_f32_e32 v91, v90
	v_mov_b32_e32 v90, v97
	v_pk_mul_f32 v[90:91], v[100:101], v[90:91]
	s_nop 0
	v_mul_f32_e32 v93, v90, v91
	v_mul_f32_e32 v90, v86, v104
	v_exp_f32_e32 v90, v90
	v_mov_b32_e32 v100, v82
	v_mul_f32_e32 v82, v87, v104
	v_exp_f32_e32 v82, v82
	v_add_f32_e32 v90, 1.0, v90
	v_rcp_f32_e32 v91, v90
	v_mov_b32_e32 v90, v86
	v_add_f32_e32 v82, 1.0, v82
	v_pk_mul_f32 v[90:91], v[100:101], v[90:91]
	s_nop 0
	v_mul_f32_e32 v96, v90, v91
	v_rcp_f32_e32 v91, v82
	v_mov_b32_e32 v100, v83
	v_mov_b32_e32 v90, v87
	v_lshl_add_u64 v[86:87], v[98:99], 0, v[114:115]
	v_pk_mul_f32 v[82:83], v[100:101], v[90:91]
	v_mov_b32_e32 v100, v84
	v_mul_f32_e32 v90, v82, v83
	v_mul_f32_e32 v82, v88, v104
	v_exp_f32_e32 v82, v82
	s_nop 0
	v_add_f32_e32 v82, 1.0, v82
	v_rcp_f32_e32 v83, v82
	v_mov_b32_e32 v82, v88
	v_pk_mul_f32 v[82:83], v[100:101], v[82:83]
	s_nop 0
	v_mul_f32_e32 v88, v82, v83
	v_mul_f32_e32 v82, v89, v104
	v_exp_f32_e32 v82, v82
	v_mov_b32_e32 v100, v85
	v_add_f32_e32 v82, 1.0, v82
; __device__ __forceinline__ unsigned pk2(float lo, float hi) { unsigned r; asm volatile("v_cvt_pk_bf16_f32 %0, %1, %2" : "=v"(r) : "v"(lo), "v"(hi)); return r; }
;     __device__ __forceinline__ void operator()(const f32x4 (&acc)[2][2][4][2], const Unit& u, int wr, int wc, int fr, int fq) const {
;     ...
; #pragma unroll
;         for (int ai = 0; ai < 2; ++ai)
; #pragma unroll
;             for (int m = 0; m < 4; ++m) { bf16_t* rowp = O + (size_t)(row0 + ai * HALF + m * 16) * DFF + col0; const float rsv = rsqrtf(rs[ai][m] * (1.f / D) + EPS);
;                 const float rs2 = rsv * rsv, nrs = -1.4426950409f * rsv;
;                 float v[8];
; #pragma unroll
;                 for (int n = 0; n < 2; ++n)
; #pragma unroll
;                     for (int j = 0; j < 4; ++j) {
;                         const float g0 = acc[ai][0][m][n][j], u0 = acc[ai][1][m][n][j];
;                         v[n * 4 + j] = (g0 * u0) * (rs2 * __builtin_amdgcn_rcpf(1.0f + __builtin_amdgcn_exp2f(g0 * nrs))); }
;                 u32x4 w; w.x = pk2(v[0], v[1]); w.y = pk2(v[2], v[3]); w.z = pk2(v[4], v[5]); w.w = pk2(v[6], v[7]);
;                 *(u32x4*)rowp = w; }
	v_rcp_f32_e32 v83, v82
	v_mov_b32_e32 v82, v89
	v_pk_mul_f32 v[82:83], v[100:101], v[82:83]
	s_nop 0
	v_mul_f32_e32 v85, v82, v83
	v_cvt_pk_bf16_f32 v82, v94, v95
	v_cvt_pk_bf16_f32 v83, v92, v93
	v_cvt_pk_bf16_f32 v84, v96, v90
	v_cvt_pk_bf16_f32 v85, v88, v85
	flat_store_dwordx4 v[86:87], v[82:85]
	v_mov_b32_e32 v86, v78
	s_nop 0
	v_fmamk_f32 v84, v160, 0x3a000000, v223
	v_cmp_gt_f32_e32 vcc, s29, v84
	v_mul_f32_e32 v85, 0x4b800000, v84
	v_mad_i64_i32 v[82:83], s[2:3], v161, s34, v[140:141]
	v_cndmask_b32_e32 v84, v84, v85, vcc
	v_rsq_f32_e32 v84, v84
	s_nop 0
	v_mul_f32_e32 v85, 0x45800000, v84
	v_cndmask_b32_e32 v84, v84, v85, vcc
	v_mul_f32_e32 v88, 0xbfb8aa3b, v84
	v_mul_f32_e32 v85, v84, v84
	v_mul_f32_e32 v84, v78, v88
	v_exp_f32_e32 v84, v84
	s_nop 0
	v_add_f32_e32 v84, 1.0, v84
	v_rcp_f32_e32 v87, v84
	v_mov_b32_e32 v84, v74
	v_mul_f32_e32 v74, v79, v88
	v_exp_f32_e32 v74, v74
	v_pk_mul_f32 v[86:87], v[84:85], v[86:87]
	v_mov_b32_e32 v84, v75
	v_mul_f32_e32 v78, v86, v87
	v_add_f32_e32 v74, 1.0, v74
	v_rcp_f32_e32 v87, v74
	v_mov_b32_e32 v86, v79
	v_pk_mul_f32 v[74:75], v[84:85], v[86:87]
	s_nop 0
	v_mul_f32_e32 v79, v74, v75
	v_mul_f32_e32 v74, v80, v88
	v_exp_f32_e32 v74, v74
	v_mov_b32_e32 v84, v76
	v_add_f32_e32 v74, 1.0, v74
	v_rcp_f32_e32 v75, v74
	v_mov_b32_e32 v74, v80
	v_pk_mul_f32 v[74:75], v[84:85], v[74:75]
	s_nop 0
	v_mul_f32_e32 v76, v74, v75
	v_mul_f32_e32 v74, v81, v88
	v_exp_f32_e32 v74, v74
	v_mov_b32_e32 v84, v77
	v_add_f32_e32 v74, 1.0, v74
	v_rcp_f32_e32 v75, v74
	v_mov_b32_e32 v74, v81
	v_pk_mul_f32 v[74:75], v[84:85], v[74:75]
	s_nop 0
	v_mul_f32_e32 v77, v74, v75
	v_mul_f32_e32 v74, v70, v88
	v_exp_f32_e32 v74, v74
	v_mov_b32_e32 v84, v66
	v_mul_f32_e32 v66, v71, v88
	v_exp_f32_e32 v66, v66
	v_add_f32_e32 v74, 1.0, v74
	v_rcp_f32_e32 v75, v74
	v_mov_b32_e32 v74, v70
	v_add_f32_e32 v66, 1.0, v66
	v_pk_mul_f32 v[74:75], v[84:85], v[74:75]
	s_nop 0
	v_mul_f32_e32 v80, v74, v75
	v_rcp_f32_e32 v75, v66
	v_mov_b32_e32 v84, v67
	v_mov_b32_e32 v74, v71
	v_lshl_add_u64 v[70:71], v[82:83], 0, v[114:115]
	v_pk_mul_f32 v[66:67], v[84:85], v[74:75]
	v_mov_b32_e32 v84, v68
	v_mul_f32_e32 v74, v66, v67
	v_mul_f32_e32 v66, v72, v88
	v_exp_f32_e32 v66, v66
	s_nop 0
	v_add_f32_e32 v66, 1.0, v66
	v_rcp_f32_e32 v67, v66
	v_mov_b32_e32 v66, v72
	v_pk_mul_f32 v[66:67], v[84:85], v[66:67]
	s_nop 0
	v_mul_f32_e32 v72, v66, v67
	v_mul_f32_e32 v66, v73, v88
	v_exp_f32_e32 v66, v66
	v_mov_b32_e32 v84, v69
	v_add_f32_e32 v66, 1.0, v66
	v_rcp_f32_e32 v67, v66
	v_mov_b32_e32 v66, v73
	v_pk_mul_f32 v[66:67], v[84:85], v[66:67]
	s_nop 0
	v_mul_f32_e32 v69, v66, v67
	v_cvt_pk_bf16_f32 v66, v78, v79
	v_cvt_pk_bf16_f32 v67, v76, v77
	v_cvt_pk_bf16_f32 v68, v80, v74
	v_cvt_pk_bf16_f32 v69, v72, v69
	flat_store_dwordx4 v[70:71], v[66:69]
	v_mov_b32_e32 v70, v62
	s_nop 0
	v_fmamk_f32 v68, v158, 0x3a000000, v223
	v_cmp_gt_f32_e32 vcc, s29, v68
	v_mul_f32_e32 v69, 0x4b800000, v68
	v_mad_i64_i32 v[66:67], s[2:3], v159, s34, v[140:141]
	v_cndmask_b32_e32 v68, v68, v69, vcc
	v_rsq_f32_e32 v68, v68
	s_nop 0
	v_mul_f32_e32 v69, 0x45800000, v68
	v_cndmask_b32_e32 v68, v68, v69, vcc
	v_mul_f32_e32 v72, 0xbfb8aa3b, v68
	v_mul_f32_e32 v69, v68, v68
	v_mul_f32_e32 v68, v62, v72
	v_exp_f32_e32 v68, v68
	s_nop 0
	v_add_f32_e32 v68, 1.0, v68
	v_rcp_f32_e32 v71, v68
	v_mov_b32_e32 v68, v58
	v_mul_f32_e32 v58, v63, v72
	v_exp_f32_e32 v58, v58
	v_pk_mul_f32 v[70:71], v[68:69], v[70:71]
	v_mov_b32_e32 v68, v59
	v_mul_f32_e32 v62, v70, v71
	v_add_f32_e32 v58, 1.0, v58
	v_rcp_f32_e32 v71, v58
	v_mov_b32_e32 v70, v63
	v_pk_mul_f32 v[58:59], v[68:69], v[70:71]
	s_nop 0
	v_mul_f32_e32 v63, v58, v59
	v_mul_f32_e32 v58, v64, v72
	v_exp_f32_e32 v58, v58
	v_mov_b32_e32 v68, v60
	v_add_f32_e32 v58, 1.0, v58
	v_rcp_f32_e32 v59, v58
	v_mov_b32_e32 v58, v64
	v_pk_mul_f32 v[58:59], v[68:69], v[58:59]
	s_nop 0
	v_mul_f32_e32 v60, v58, v59
	v_mul_f32_e32 v58, v65, v72
	v_exp_f32_e32 v58, v58
	v_mov_b32_e32 v68, v61
	v_add_f32_e32 v58, 1.0, v58
	v_rcp_f32_e32 v59, v58
	v_mov_b32_e32 v58, v65
	v_pk_mul_f32 v[58:59], v[68:69], v[58:59]
	s_nop 0
	v_mul_f32_e32 v61, v58, v59
	v_mul_f32_e32 v58, v54, v72
	v_exp_f32_e32 v58, v58
	v_mov_b32_e32 v68, v50
	v_mul_f32_e32 v50, v55, v72
	v_exp_f32_e32 v50, v50
	v_add_f32_e32 v58, 1.0, v58
	v_rcp_f32_e32 v59, v58
	v_mov_b32_e32 v58, v54
	v_add_f32_e32 v50, 1.0, v50
	v_pk_mul_f32 v[58:59], v[68:69], v[58:59]
	s_nop 0
	v_mul_f32_e32 v64, v58, v59
	v_rcp_f32_e32 v59, v50
	v_mov_b32_e32 v68, v51
	v_mov_b32_e32 v58, v55
	v_lshl_add_u64 v[54:55], v[66:67], 0, v[114:115]
	v_pk_mul_f32 v[50:51], v[68:69], v[58:59]
	v_mov_b32_e32 v68, v52
	v_mul_f32_e32 v58, v50, v51
	v_mul_f32_e32 v50, v56, v72
	v_exp_f32_e32 v50, v50
	s_nop 0
	v_add_f32_e32 v50, 1.0, v50
	v_rcp_f32_e32 v51, v50
	v_mov_b32_e32 v50, v56
	v_pk_mul_f32 v[50:51], v[68:69], v[50:51]
	s_nop 0
	v_mul_f32_e32 v56, v50, v51
	v_mul_f32_e32 v50, v57, v72
	v_exp_f32_e32 v50, v50
	v_mov_b32_e32 v68, v53
	v_add_f32_e32 v50, 1.0, v50
	v_rcp_f32_e32 v51, v50
	v_mov_b32_e32 v50, v57
	v_pk_mul_f32 v[50:51], v[68:69], v[50:51]
	s_nop 0
	v_mul_f32_e32 v53, v50, v51
	v_cvt_pk_bf16_f32 v50, v62, v63
	v_cvt_pk_bf16_f32 v51, v60, v61
	v_cvt_pk_bf16_f32 v52, v64, v58
	v_cvt_pk_bf16_f32 v53, v56, v53
	flat_store_dwordx4 v[54:55], v[50:53]
	v_mov_b32_e32 v54, v46
	s_nop 0
	v_fmamk_f32 v52, v156, 0x3a000000, v223
	v_cmp_gt_f32_e32 vcc, s29, v52
	v_mul_f32_e32 v53, 0x4b800000, v52
	v_mad_i64_i32 v[50:51], s[2:3], v157, s34, v[140:141]
	v_cndmask_b32_e32 v52, v52, v53, vcc
	v_rsq_f32_e32 v52, v52
	s_nop 0
	v_mul_f32_e32 v53, 0x45800000, v52
	v_cndmask_b32_e32 v52, v52, v53, vcc
	v_mul_f32_e32 v56, 0xbfb8aa3b, v52
; __device__ __forceinline__ unsigned pk2(float lo, float hi) { unsigned r; asm volatile("v_cvt_pk_bf16_f32 %0, %1, %2" : "=v"(r) : "v"(lo), "v"(hi)); return r; }
;     __device__ __forceinline__ void operator()(const f32x4 (&acc)[2][2][4][2], const Unit& u, int wr, int wc, int fr, int fq) const {
;     ...
; #pragma unroll
;         for (int ai = 0; ai < 2; ++ai)
; #pragma unroll
;             for (int m = 0; m < 4; ++m) { bf16_t* rowp = O + (size_t)(row0 + ai * HALF + m * 16) * DFF + col0; const float rsv = rsqrtf(rs[ai][m] * (1.f / D) + EPS);
;                 const float rs2 = rsv * rsv, nrs = -1.4426950409f * rsv;
;                 float v[8];
; #pragma unroll
;                 for (int n = 0; n < 2; ++n)
; #pragma unroll
;                     for (int j = 0; j < 4; ++j) {
;                         const float g0 = acc[ai][0][m][n][j], u0 = acc[ai][1][m][n][j];
;                         v[n * 4 + j] = (g0 * u0) * (rs2 * __builtin_amdgcn_rcpf(1.0f + __builtin_amdgcn_exp2f(g0 * nrs))); }
;                 u32x4 w; w.x = pk2(v[0], v[1]); w.y = pk2(v[2], v[3]); w.z = pk2(v[4], v[5]); w.w = pk2(v[6], v[7]);
;                 *(u32x4*)rowp = w; }
	v_mul_f32_e32 v53, v52, v52
	v_mul_f32_e32 v52, v46, v56
	v_exp_f32_e32 v52, v52
	s_nop 0
	v_add_f32_e32 v52, 1.0, v52
	v_rcp_f32_e32 v55, v52
	v_mov_b32_e32 v52, v42
	v_mul_f32_e32 v42, v47, v56
	v_exp_f32_e32 v42, v42
	v_pk_mul_f32 v[54:55], v[52:53], v[54:55]
	v_mov_b32_e32 v52, v43
	v_mul_f32_e32 v46, v54, v55
	v_add_f32_e32 v42, 1.0, v42
	v_rcp_f32_e32 v55, v42
	v_mov_b32_e32 v54, v47
	v_pk_mul_f32 v[42:43], v[52:53], v[54:55]
	s_nop 0
	v_mul_f32_e32 v47, v42, v43
	v_mul_f32_e32 v42, v48, v56
	v_exp_f32_e32 v42, v42
	v_mov_b32_e32 v52, v44
	v_add_f32_e32 v42, 1.0, v42
	v_rcp_f32_e32 v43, v42
	v_mov_b32_e32 v42, v48
	v_pk_mul_f32 v[42:43], v[52:53], v[42:43]
	s_nop 0
	v_mul_f32_e32 v44, v42, v43
	v_mul_f32_e32 v42, v49, v56
	v_exp_f32_e32 v42, v42
	v_mov_b32_e32 v52, v45
	v_add_f32_e32 v42, 1.0, v42
	v_rcp_f32_e32 v43, v42
	v_mov_b32_e32 v42, v49
	v_pk_mul_f32 v[42:43], v[52:53], v[42:43]
	s_nop 0
	v_mul_f32_e32 v45, v42, v43
	v_mul_f32_e32 v42, v38, v56
	v_exp_f32_e32 v42, v42
	v_mov_b32_e32 v52, v34
	v_mul_f32_e32 v34, v39, v56
	v_exp_f32_e32 v34, v34
	v_add_f32_e32 v42, 1.0, v42
	v_rcp_f32_e32 v43, v42
	v_mov_b32_e32 v42, v38
	v_add_f32_e32 v34, 1.0, v34
	v_pk_mul_f32 v[42:43], v[52:53], v[42:43]
	s_nop 0
	v_mul_f32_e32 v48, v42, v43
	v_rcp_f32_e32 v43, v34
	v_mov_b32_e32 v52, v35
	v_mov_b32_e32 v42, v39
	v_lshl_add_u64 v[38:39], v[50:51], 0, v[114:115]
	v_pk_mul_f32 v[34:35], v[52:53], v[42:43]
	v_mov_b32_e32 v52, v36
	v_mul_f32_e32 v42, v34, v35
	v_mul_f32_e32 v34, v40, v56
	v_exp_f32_e32 v34, v34
	s_nop 0
	v_add_f32_e32 v34, 1.0, v34
	v_rcp_f32_e32 v35, v34
	v_mov_b32_e32 v34, v40
	v_pk_mul_f32 v[34:35], v[52:53], v[34:35]
	s_nop 0
	v_mul_f32_e32 v40, v34, v35
	v_mul_f32_e32 v34, v41, v56
	v_exp_f32_e32 v34, v34
	v_mov_b32_e32 v52, v37
	v_add_f32_e32 v34, 1.0, v34
	v_rcp_f32_e32 v35, v34
	v_mov_b32_e32 v34, v41
	v_pk_mul_f32 v[34:35], v[52:53], v[34:35]
	s_nop 0
	v_mul_f32_e32 v37, v34, v35
	v_cvt_pk_bf16_f32 v34, v46, v47
	v_cvt_pk_bf16_f32 v35, v44, v45
	v_cvt_pk_bf16_f32 v36, v48, v42
	v_cvt_pk_bf16_f32 v37, v40, v37
	flat_store_dwordx4 v[38:39], v[34:37]
	v_mov_b32_e32 v38, v30
	s_nop 0
	v_fmamk_f32 v36, v154, 0x3a000000, v223
	v_cmp_gt_f32_e32 vcc, s29, v36
	v_mul_f32_e32 v37, 0x4b800000, v36
	v_mad_i64_i32 v[34:35], s[2:3], v155, s34, v[140:141]
	v_cndmask_b32_e32 v36, v36, v37, vcc
	v_rsq_f32_e32 v36, v36
	s_nop 0
	v_mul_f32_e32 v37, 0x45800000, v36
	v_cndmask_b32_e32 v36, v36, v37, vcc
	v_mul_f32_e32 v40, 0xbfb8aa3b, v36
	v_mul_f32_e32 v37, v36, v36
	v_mul_f32_e32 v36, v30, v40
	v_exp_f32_e32 v36, v36
	s_nop 0
	v_add_f32_e32 v36, 1.0, v36
	v_rcp_f32_e32 v39, v36
	v_mov_b32_e32 v36, v26
	v_mul_f32_e32 v26, v31, v40
	v_exp_f32_e32 v26, v26
	v_pk_mul_f32 v[38:39], v[36:37], v[38:39]
	v_mov_b32_e32 v36, v27
	v_mul_f32_e32 v30, v38, v39
	v_add_f32_e32 v26, 1.0, v26
	v_rcp_f32_e32 v39, v26
	v_mov_b32_e32 v38, v31
	v_pk_mul_f32 v[26:27], v[36:37], v[38:39]
	s_nop 0
	v_mul_f32_e32 v31, v26, v27
	v_mul_f32_e32 v26, v32, v40
	v_exp_f32_e32 v26, v26
	v_mov_b32_e32 v36, v28
	v_add_f32_e32 v26, 1.0, v26
	v_rcp_f32_e32 v27, v26
	v_mov_b32_e32 v26, v32
	v_pk_mul_f32 v[26:27], v[36:37], v[26:27]
	s_nop 0
	v_mul_f32_e32 v28, v26, v27
	v_mul_f32_e32 v26, v33, v40
	v_exp_f32_e32 v26, v26
	v_mov_b32_e32 v36, v29
	v_add_f32_e32 v26, 1.0, v26
	v_rcp_f32_e32 v27, v26
	v_mov_b32_e32 v26, v33
	v_pk_mul_f32 v[26:27], v[36:37], v[26:27]
	s_nop 0
	v_mul_f32_e32 v29, v26, v27
	v_mul_f32_e32 v26, v22, v40
	v_exp_f32_e32 v26, v26
	v_mov_b32_e32 v36, v18
	v_mul_f32_e32 v18, v23, v40
	v_exp_f32_e32 v18, v18
	v_add_f32_e32 v26, 1.0, v26
	v_rcp_f32_e32 v27, v26
	v_mov_b32_e32 v26, v22
	v_add_f32_e32 v18, 1.0, v18
	v_pk_mul_f32 v[26:27], v[36:37], v[26:27]
	s_nop 0
	v_mul_f32_e32 v32, v26, v27
; __device__ __forceinline__ unsigned pk2(float lo, float hi) { unsigned r; asm volatile("v_cvt_pk_bf16_f32 %0, %1, %2" : "=v"(r) : "v"(lo), "v"(hi)); return r; }
; #define PG8_WAIT_V(n) asm volatile("s_waitcnt vmcnt(" #n ")" ::: "memory")
; #define PG8_BAR __builtin_amdgcn_s_barrier()
; template <class Epi, class Sched, bool ALIGN_EPI = false, bool SP2 = false>
; __device__ __forceinline__ void gemm_phase(PG8_LAS unsigned char* lds, const Gemm g, const Sched& S, const Epi& E) {
;     ...
;         if (!has_next) break;
;         if (cur.ks != -2) {
; #pragma unroll
;         for (int a = 0; a < 2; ++a)
; #pragma unroll
;             for (int b = 0; b < 2; ++b)
; #pragma unroll
;                 for (int m = 0; m < 4; ++m)
; #pragma unroll
;                     for (int n = 0; n < 2; ++n) acc[a][b][m][n] = (f32x4){0.f, 0.f, 0.f, 0.f};
;         }
;         cur = nxt; cA = nA; cB = nB; ++ui;
;         if constexpr (ALIGN_EPI) { if (wr == 1) PG8_BAR; }
;     }
;     PG8_WAIT_V(0);
;     if constexpr (!ALIGN_EPI) { if (wr == 0) PG8_BAR; }
;     PG8_BAR;
;     __device__ __forceinline__ void operator()(const f32x4 (&acc)[2][2][4][2], const Unit& u, int wr, int wc, int fr, int fq) const {
;     ...
; #pragma unroll
;         for (int ai = 0; ai < 2; ++ai)
; #pragma unroll
;             for (int m = 0; m < 4; ++m) { bf16_t* rowp = O + (size_t)(row0 + ai * HALF + m * 16) * DFF + col0; const float rsv = rsqrtf(rs[ai][m] * (1.f / D) + EPS);
;                 const float rs2 = rsv * rsv, nrs = -1.4426950409f * rsv;
;                 float v[8];
; #pragma unroll
;                 for (int n = 0; n < 2; ++n)
; #pragma unroll
;                     for (int j = 0; j < 4; ++j) {
;                         const float g0 = acc[ai][0][m][n][j], u0 = acc[ai][1][m][n][j];
;                         v[n * 4 + j] = (g0 * u0) * (rs2 * __builtin_amdgcn_rcpf(1.0f + __builtin_amdgcn_exp2f(g0 * nrs))); }
;                 u32x4 w; w.x = pk2(v[0], v[1]); w.y = pk2(v[2], v[3]); w.z = pk2(v[4], v[5]); w.w = pk2(v[6], v[7]);
;                 *(u32x4*)rowp = w; }
	v_rcp_f32_e32 v27, v18
	v_mov_b32_e32 v36, v19
	v_mov_b32_e32 v26, v23
	v_lshl_add_u64 v[22:23], v[34:35], 0, v[114:115]
	v_pk_mul_f32 v[18:19], v[36:37], v[26:27]
	v_mov_b32_e32 v36, v20
	v_mul_f32_e32 v26, v18, v19
	v_mul_f32_e32 v18, v24, v40
	v_exp_f32_e32 v18, v18
	s_nop 0
	v_add_f32_e32 v18, 1.0, v18
	v_rcp_f32_e32 v19, v18
	v_mov_b32_e32 v18, v24
	v_pk_mul_f32 v[18:19], v[36:37], v[18:19]
	s_nop 0
	v_mul_f32_e32 v24, v18, v19
	v_mul_f32_e32 v18, v25, v40
	v_exp_f32_e32 v18, v18
	v_mov_b32_e32 v36, v21
	v_add_f32_e32 v18, 1.0, v18
	v_rcp_f32_e32 v19, v18
	v_mov_b32_e32 v18, v25
	v_pk_mul_f32 v[18:19], v[36:37], v[18:19]
	s_nop 0
	v_mul_f32_e32 v21, v18, v19
	v_cvt_pk_bf16_f32 v18, v30, v31
	v_cvt_pk_bf16_f32 v19, v28, v29
	v_cvt_pk_bf16_f32 v20, v32, v26
	v_cvt_pk_bf16_f32 v21, v24, v21
	flat_store_dwordx4 v[22:23], v[18:21]
	v_mov_b32_e32 v22, v14
	s_nop 0
	v_fmamk_f32 v20, v152, 0x3a000000, v223
	v_cmp_gt_f32_e32 vcc, s29, v20
	v_mul_f32_e32 v21, 0x4b800000, v20
	v_mad_i64_i32 v[18:19], s[2:3], v153, s34, v[140:141]
	v_cndmask_b32_e32 v20, v20, v21, vcc
	v_rsq_f32_e32 v20, v20
	s_nop 0
	v_mul_f32_e32 v21, 0x45800000, v20
	v_cndmask_b32_e32 v20, v20, v21, vcc
	v_mul_f32_e32 v24, 0xbfb8aa3b, v20
	v_mul_f32_e32 v21, v20, v20
	v_mul_f32_e32 v20, v14, v24
	v_exp_f32_e32 v20, v20
	s_andn2_b64 vcc, exec, s[40:41]
	v_add_f32_e32 v20, 1.0, v20
	v_rcp_f32_e32 v23, v20
	v_mov_b32_e32 v20, v10
	v_mul_f32_e32 v10, v15, v24
	v_exp_f32_e32 v10, v10
	v_pk_mul_f32 v[22:23], v[20:21], v[22:23]
	v_mov_b32_e32 v20, v11
	v_mul_f32_e32 v14, v22, v23
	v_add_f32_e32 v10, 1.0, v10
	v_rcp_f32_e32 v23, v10
	v_mov_b32_e32 v22, v15
	v_pk_mul_f32 v[10:11], v[20:21], v[22:23]
	s_nop 0
	v_mul_f32_e32 v15, v10, v11
	v_mul_f32_e32 v10, v16, v24
	v_exp_f32_e32 v10, v10
	v_mov_b32_e32 v20, v12
	v_add_f32_e32 v10, 1.0, v10
	v_rcp_f32_e32 v11, v10
	v_mov_b32_e32 v10, v16
	v_pk_mul_f32 v[10:11], v[20:21], v[10:11]
	s_nop 0
	v_mul_f32_e32 v12, v10, v11
	v_mul_f32_e32 v10, v17, v24
	v_exp_f32_e32 v10, v10
	v_mov_b32_e32 v20, v13
	v_add_f32_e32 v10, 1.0, v10
	v_rcp_f32_e32 v11, v10
	v_mov_b32_e32 v10, v17
	v_pk_mul_f32 v[10:11], v[20:21], v[10:11]
	s_nop 0
	v_mul_f32_e32 v13, v10, v11
	v_mul_f32_e32 v10, v6, v24
	v_exp_f32_e32 v10, v10
	v_mov_b32_e32 v20, v2
	v_mul_f32_e32 v2, v7, v24
	v_exp_f32_e32 v2, v2
	v_add_f32_e32 v10, 1.0, v10
	v_rcp_f32_e32 v11, v10
	v_mov_b32_e32 v10, v6
	v_add_f32_e32 v2, 1.0, v2
	v_pk_mul_f32 v[10:11], v[20:21], v[10:11]
	s_nop 0
	v_mul_f32_e32 v16, v10, v11
	v_rcp_f32_e32 v11, v2
	v_mov_b32_e32 v20, v3
	v_mov_b32_e32 v10, v7
	v_lshl_add_u64 v[6:7], v[18:19], 0, v[114:115]
	v_pk_mul_f32 v[2:3], v[20:21], v[10:11]
	v_mov_b32_e32 v20, v4
	v_mul_f32_e32 v10, v2, v3
	v_mul_f32_e32 v2, v8, v24
	v_exp_f32_e32 v2, v2
	s_nop 0
	v_add_f32_e32 v2, 1.0, v2
	v_rcp_f32_e32 v3, v2
	v_mov_b32_e32 v2, v8
	v_pk_mul_f32 v[2:3], v[20:21], v[2:3]
	s_nop 0
	v_mul_f32_e32 v8, v2, v3
	v_mul_f32_e32 v2, v9, v24
	v_exp_f32_e32 v2, v2
	v_mov_b32_e32 v20, v5
	v_add_f32_e32 v2, 1.0, v2
	v_rcp_f32_e32 v3, v2
	v_mov_b32_e32 v2, v9
	v_pk_mul_f32 v[2:3], v[20:21], v[2:3]
	s_nop 0
	v_mul_f32_e32 v5, v2, v3
	v_cvt_pk_bf16_f32 v2, v14, v15
	v_cvt_pk_bf16_f32 v3, v12, v13
	v_cvt_pk_bf16_f32 v4, v16, v10
	v_cvt_pk_bf16_f32 v5, v8, v5
	flat_store_dwordx4 v[6:7], v[2:5]
	s_cbranch_vccnz .LBB0_1483
	s_andn2_b64 vcc, exec, s[14:15]
	s_cbranch_vccnz .LBB0_1482
	s_barrier
	s_branch .LBB0_1482
	s_nop 0
	s_nop 0
	s_nop 0
	s_nop 0
.LBB0_1493:
	s_waitcnt vmcnt(0)
	v_readlane_b32 s24, v250, 16
	v_readlane_b32 s36, v250, 18
	v_readlane_b32 s42, v250, 20
	v_readlane_b32 s40, v250, 22
	v_readlane_b32 s25, v250, 17
	v_readlane_b32 s37, v250, 19
	v_readlane_b32 s43, v250, 21
	v_readlane_b32 s41, v250, 23
	s_barrier
